# GEMM K-loops (in-proj, gate/up, down): LDS-DMA addresses via SGPR base + 32-bit VGPR offset instead of 64-bit VALU adds
# baseline (speedup 1.0000x reference)
; #define PG8_STAGE(bufoff, gbase, voff) do { _Pragma("unroll") for (int _i = 0; _i < 2; ++_i) \
;         __builtin_amdgcn_global_load_lds((const unsigned*)((const char*)(gbase) + (voff)[_i]), (PG8_LAS unsigned*)(lds + (bufoff) + ldsw + _i * 8192), 16, 0, 0); } while (0)
; #define PG8_LDA(dst, b, h) do { _Pragma("unroll") for (int m = 0; m < 4; ++m) _Pragma("unroll") for (int k = 0; k < 2; ++k) dst[m][k] = *(const PG8_LAS bf16x8*)(lds + PG8_SA(b, h) + aoff + m * 2048 + k * 1024); } while (0)
; #define PG8_LDB(dst, b, h) do { _Pragma("unroll") for (int n = 0; n < 2; ++n) _Pragma("unroll") for (int k = 0; k < 2; ++k) dst[n][k] = *(const PG8_LAS bf16x8*)(lds + PG8_SB(b, h) + boff + n * 2048 + k * 1024); } while (0)
; #define PG8_WAIT_V(n) asm volatile("s_waitcnt vmcnt(" #n ")" ::: "memory")
; #define PG8_BAR __builtin_amdgcn_s_barrier()
; template <class Epi, class Sched, bool ALIGN_EPI = false, bool SP2 = false, bool F16 = false>
; __device__ __forceinline__ void gemm_phase(PG8_LAS unsigned char* lds, const Gemm g, const Sched& S, const Epi& E) {
;     ...
;         const bool has_next = S.next(ui + 1, nxt);
;         const char* nA = has_next ? (const char*)g.A + (size_t)nxt.pm * tstep : cA; const char* nB = has_next ? (const char*)g.Bt + (size_t)nxt.pn * tstep + (nxt.pm >= g.mhalf ? g.bstride : (size_t)0) : cB;
;         for (int t = 0; t < nt; t += 2) {
;             if constexpr (Epi::KHOOK) { if (t == 4 || t == 10) E.khook(acc, cur, t, wr, fr); }
;             const bool last = (t == nt - 2);
;             const char* a1 = cA + (size_t)(t + 1) * kstep;
;             const char* a2 = last ? nA : cA + (size_t)(t + 2) * kstep; const char* b2 = last ? nB : cB + (size_t)(t + 2) * kstep;
;             const char* a3 = a2 + kstep; const char* b3 = b2 + kstep;
;             if (last && has_next) S.a_ready(nxt);
;             if constexpr (SP2) {
;             PG8_LDB(B0, 0, 0); PG8_LDB(B1, 0, 1); PG8_SCHED; PG8_LDA(At, 0, 0); PG8_STAGE(PG8_SA(1, 1), a1 + hstep, voffA);
;             PG8_WAIT_V(8); PG8_WAIT_L(0); PG8_BAR; PG8_MMA(0, 0, At, B0); PG8_MMA(0, 1, At, B1); PG8_BAR; PG8_SCHED;
;             PG8_LDA(At, 0, 1); PG8_STAGE(PG8_SB(0, 0), b2, voffB); PG8_STAGE(PG8_SB(0, 1), b2 + hstep, voffB); PG8_STAGE(PG8_SA(0, 0), a2, voffA);
;             PG8_WAIT_V(8); PG8_WAIT_L(0); PG8_BAR; PG8_MMA(1, 0, At, B0); PG8_MMA(1, 1, At, B1); PG8_BAR; PG8_SCHED;
.LBB0_256:
	s_add_u32 s42, s0, 0xfffc0080
	s_addc_u32 s43, s1, -1
	s_add_i32 s68, 0, 0x10000
	s_cmp_eq_u32 s67, 12
	s_cselect_b32 s55, s4, s43
	s_cselect_b32 s54, s5, s42
	v_add_u32_e32 v159, s68, v239
	s_cselect_b32 s43, s7, s61
	s_cselect_b32 s42, s34, s59
	s_add_i32 s70, 0, 0x14000
	ds_read_b128 v[130:133], v159
	ds_read_b128 v[134:137], v159 offset:1024
	ds_read_b128 v[138:141], v159 offset:2048
	ds_read_b128 v[162:165], v159 offset:3072
	v_add_u32_e32 v159, s70, v239
	ds_read_b128 v[166:169], v159
	ds_read_b128 v[170:173], v159 offset:1024
	ds_read_b128 v[186:189], v159 offset:2048
	ds_read_b128 v[190:193], v159 offset:3072
	s_add_i32 m0, s21, 0xc000
	ds_read_b128 v[194:197], v240
	ds_read_b128 v[198:201], v240 offset:1024
	ds_read_b128 v[202:205], v240 offset:2048
	ds_read_b128 v[206:209], v240 offset:3072
	ds_read_b128 v[210:213], v240 offset:4096
	ds_read_b128 v[214:217], v240 offset:5120
	ds_read_b128 v[218:221], v240 offset:6144
	ds_read_b128 v[222:225], v240 offset:7168
	global_load_lds_dwordx4 v154, s[0:1]
	s_add_i32 m0, s21, 0xe000
	s_nop 0
	global_load_lds_dwordx4 v156, s[0:1]
	s_waitcnt vmcnt(8)
	s_waitcnt lgkmcnt(0)
	s_barrier
	s_setprio 1
	s_waitcnt lgkmcnt(0)
	v_mfma_f32_16x16x32_f16 v[124:127], v[130:133], v[194:197], v[124:127]
	v_mfma_f32_16x16x32_f16 v[120:123], v[138:141], v[194:197], v[120:123]
	v_mfma_f32_16x16x32_f16 v[116:119], v[130:133], v[202:205], v[116:119]
	v_mfma_f32_16x16x32_f16 v[112:115], v[138:141], v[202:205], v[112:115]
	v_mfma_f32_16x16x32_f16 v[108:111], v[130:133], v[210:213], v[108:111]
	v_mfma_f32_16x16x32_f16 v[104:107], v[138:141], v[210:213], v[104:107]
	v_mfma_f32_16x16x32_f16 v[100:103], v[130:133], v[218:221], v[100:103]
	v_mfma_f32_16x16x32_f16 v[96:99], v[138:141], v[218:221], v[96:99]
	v_mfma_f32_16x16x32_f16 v[124:127], v[134:137], v[198:201], v[124:127]
	v_mfma_f32_16x16x32_f16 v[120:123], v[162:165], v[198:201], v[120:123]
	v_mfma_f32_16x16x32_f16 v[116:119], v[134:137], v[206:209], v[116:119]
	v_mfma_f32_16x16x32_f16 v[112:115], v[162:165], v[206:209], v[112:115]
	v_mfma_f32_16x16x32_f16 v[108:111], v[134:137], v[214:217], v[108:111]
	v_mfma_f32_16x16x32_f16 v[104:107], v[162:165], v[214:217], v[104:107]
	v_mfma_f32_16x16x32_f16 v[100:103], v[134:137], v[222:225], v[100:103]
	v_mfma_f32_16x16x32_f16 v[96:99], v[162:165], v[222:225], v[96:99]
	s_setprio 0
	s_setprio 1
	v_mfma_f32_16x16x32_f16 v[60:63], v[166:169], v[194:197], v[60:63]
	v_mfma_f32_16x16x32_f16 v[56:59], v[186:189], v[194:197], v[56:59]
	v_mfma_f32_16x16x32_f16 v[52:55], v[166:169], v[202:205], v[52:55]
	v_mfma_f32_16x16x32_f16 v[48:51], v[186:189], v[202:205], v[48:51]
	v_mfma_f32_16x16x32_f16 v[44:47], v[166:169], v[210:213], v[44:47]
	v_mfma_f32_16x16x32_f16 v[40:43], v[186:189], v[210:213], v[40:43]
	v_mfma_f32_16x16x32_f16 v[36:39], v[166:169], v[218:221], v[36:39]
	v_mfma_f32_16x16x32_f16 v[32:35], v[186:189], v[218:221], v[32:35]
	v_mfma_f32_16x16x32_f16 v[60:63], v[170:173], v[198:201], v[60:63]
	v_mfma_f32_16x16x32_f16 v[56:59], v[190:193], v[198:201], v[56:59]
	v_mfma_f32_16x16x32_f16 v[52:55], v[170:173], v[206:209], v[52:55]
	v_mfma_f32_16x16x32_f16 v[48:51], v[190:193], v[206:209], v[48:51]
	v_mfma_f32_16x16x32_f16 v[44:47], v[170:173], v[214:217], v[44:47]
	v_mfma_f32_16x16x32_f16 v[40:43], v[190:193], v[214:217], v[40:43]
	v_mfma_f32_16x16x32_f16 v[36:39], v[170:173], v[222:225], v[36:39]
	v_mfma_f32_16x16x32_f16 v[32:35], v[190:193], v[222:225], v[32:35]
	s_setprio 0
	s_barrier
	s_add_u32 s98, s42, s16
	s_addc_u32 s99, s43, s17
	s_add_u32 s100, s54, s16
	s_addc_u32 s101, s55, s17
	s_add_i32 s68, s68, s20
	s_mov_b32 m0, s68
	ds_read_b128 v[194:197], v240 offset:16384
	ds_read_b128 v[198:201], v240 offset:17408
	ds_read_b128 v[202:205], v240 offset:18432
	ds_read_b128 v[206:209], v240 offset:19456
	ds_read_b128 v[210:213], v240 offset:20480
	ds_read_b128 v[214:217], v240 offset:21504
	ds_read_b128 v[218:221], v240 offset:22528
	ds_read_b128 v[222:225], v240 offset:23552
	global_load_lds_dwordx4 v146, s[42:43]
	s_add_i32 m0, s68, 0x2000
	s_add_u32 s68, s42, 0x40000
	s_addc_u32 s69, s43, 0
	s_add_i32 s70, s70, s20
	global_load_lds_dwordx4 v142, s[42:43]
	s_mov_b32 m0, s70
	s_nop 0
	global_load_lds_dwordx4 v146, s[68:69]
	s_add_i32 m0, s70, 0x2000
	s_nop 0
	global_load_lds_dwordx4 v142, s[68:69]
	s_mov_b32 m0, s21
	s_nop 0
	global_load_lds_dwordx4 v148, s[54:55]
	s_mov_b32 m0, s14
	s_nop 0
	global_load_lds_dwordx4 v144, s[54:55]
	s_waitcnt vmcnt(8)
	s_waitcnt lgkmcnt(0)
	s_barrier
	s_setprio 1
	s_waitcnt lgkmcnt(0)
	v_mfma_f32_16x16x32_f16 v[92:95], v[130:133], v[194:197], v[92:95]
	v_mfma_f32_16x16x32_f16 v[88:91], v[138:141], v[194:197], v[88:91]
	v_mfma_f32_16x16x32_f16 v[84:87], v[130:133], v[202:205], v[84:87]
	v_mfma_f32_16x16x32_f16 v[80:83], v[138:141], v[202:205], v[80:83]
	v_mfma_f32_16x16x32_f16 v[76:79], v[130:133], v[210:213], v[76:79]
	v_mfma_f32_16x16x32_f16 v[72:75], v[138:141], v[210:213], v[72:75]
	v_mfma_f32_16x16x32_f16 v[68:71], v[130:133], v[218:221], v[68:71]
	v_mfma_f32_16x16x32_f16 v[64:67], v[138:141], v[218:221], v[64:67]
	v_mfma_f32_16x16x32_f16 v[92:95], v[134:137], v[198:201], v[92:95]
	v_mfma_f32_16x16x32_f16 v[88:91], v[162:165], v[198:201], v[88:91]
	v_mfma_f32_16x16x32_f16 v[84:87], v[134:137], v[206:209], v[84:87]
	v_mfma_f32_16x16x32_f16 v[80:83], v[162:165], v[206:209], v[80:83]
	v_mfma_f32_16x16x32_f16 v[76:79], v[134:137], v[214:217], v[76:79]
	v_mfma_f32_16x16x32_f16 v[72:75], v[162:165], v[214:217], v[72:75]
	v_mfma_f32_16x16x32_f16 v[68:71], v[134:137], v[222:225], v[68:71]
	v_mfma_f32_16x16x32_f16 v[64:67], v[162:165], v[222:225], v[64:67]
	s_setprio 0
	s_setprio 1
	v_mfma_f32_16x16x32_f16 v[28:31], v[166:169], v[194:197], v[28:31]
	v_mfma_f32_16x16x32_f16 v[24:27], v[186:189], v[194:197], v[24:27]
	v_mfma_f32_16x16x32_f16 v[20:23], v[166:169], v[202:205], v[20:23]
	v_mfma_f32_16x16x32_f16 v[16:19], v[186:189], v[202:205], v[16:19]
	v_mfma_f32_16x16x32_f16 v[12:15], v[166:169], v[210:213], v[12:15]
	v_mfma_f32_16x16x32_f16 v[8:11], v[186:189], v[210:213], v[8:11]
	v_mfma_f32_16x16x32_f16 v[4:7], v[166:169], v[218:221], v[4:7]
	v_mfma_f32_16x16x32_f16 v[0:3], v[186:189], v[218:221], v[0:3]
	v_mfma_f32_16x16x32_f16 v[28:31], v[170:173], v[198:201], v[28:31]
	v_mfma_f32_16x16x32_f16 v[24:27], v[190:193], v[198:201], v[24:27]
	v_mfma_f32_16x16x32_f16 v[20:23], v[170:173], v[206:209], v[20:23]
	v_mfma_f32_16x16x32_f16 v[16:19], v[190:193], v[206:209], v[16:19]
	v_mfma_f32_16x16x32_f16 v[12:15], v[170:173], v[214:217], v[12:15]
	v_mfma_f32_16x16x32_f16 v[8:11], v[190:193], v[214:217], v[8:11]
	v_mfma_f32_16x16x32_f16 v[4:7], v[170:173], v[222:225], v[4:7]
	v_mfma_f32_16x16x32_f16 v[0:3], v[190:193], v[222:225], v[0:3]
	s_setprio 0
	s_barrier
; #define PG8_STAGE(bufoff, gbase, voff) do { _Pragma("unroll") for (int _i = 0; _i < 2; ++_i) \
;         __builtin_amdgcn_global_load_lds((const unsigned*)((const char*)(gbase) + (voff)[_i]), (PG8_LAS unsigned*)(lds + (bufoff) + ldsw + _i * 8192), 16, 0, 0); } while (0)
; #define PG8_LDA(dst, b, h) do { _Pragma("unroll") for (int m = 0; m < 4; ++m) _Pragma("unroll") for (int k = 0; k < 2; ++k) dst[m][k] = *(const PG8_LAS bf16x8*)(lds + PG8_SA(b, h) + aoff + m * 2048 + k * 1024); } while (0)
; #define PG8_LDB(dst, b, h) do { _Pragma("unroll") for (int n = 0; n < 2; ++n) _Pragma("unroll") for (int k = 0; k < 2; ++k) dst[n][k] = *(const PG8_LAS bf16x8*)(lds + PG8_SB(b, h) + boff + n * 2048 + k * 1024); } while (0)
; #define PG8_WAIT_V(n) asm volatile("s_waitcnt vmcnt(" #n ")" ::: "memory")
; template <class Epi, class Sched, bool ALIGN_EPI = false, bool SP2 = false, bool F16 = false>
; __device__ __forceinline__ void gemm_phase(PG8_LAS unsigned char* lds, const Gemm g, const Sched& S, const Epi& E) {
;     ...
;             const char* a1 = cA + (size_t)(t + 1) * kstep;
;             const char* a2 = last ? nA : cA + (size_t)(t + 2) * kstep; const char* b2 = last ? nB : cB + (size_t)(t + 2) * kstep;
;             const char* a3 = a2 + kstep; const char* b3 = b2 + kstep;
;             if (last && has_next) S.a_ready(nxt);
;             if constexpr (SP2) {
;             PG8_LDB(B0, 0, 0); PG8_LDB(B1, 0, 1); PG8_SCHED; PG8_LDA(At, 0, 0); PG8_STAGE(PG8_SA(1, 1), a1 + hstep, voffA);
;             PG8_WAIT_V(8); PG8_WAIT_L(0); PG8_BAR; PG8_MMA(0, 0, At, B0); PG8_MMA(0, 1, At, B1); PG8_BAR; PG8_SCHED;
;             PG8_LDA(At, 0, 1); PG8_STAGE(PG8_SB(0, 0), b2, voffB); PG8_STAGE(PG8_SB(0, 1), b2 + hstep, voffB); PG8_STAGE(PG8_SA(0, 0), a2, voffA);
;             PG8_WAIT_V(8); PG8_WAIT_L(0); PG8_BAR; PG8_MMA(1, 0, At, B0); PG8_MMA(1, 1, At, B1); PG8_BAR; PG8_SCHED;
;             PG8_LDB(B0, 1, 0); PG8_LDB(B1, 1, 1); PG8_SCHED; PG8_LDA(At, 1, 0); PG8_STAGE(PG8_SA(0, 1), a2 + hstep, voffA);
;             PG8_WAIT_V(8); PG8_WAIT_L(0); PG8_BAR; PG8_MMA(0, 0, At, B0); PG8_MMA(0, 1, At, B1); PG8_BAR; PG8_SCHED;
;             PG8_LDA(At, 1, 1); PG8_STAGE(PG8_SB(1, 0), b3, voffB); PG8_STAGE(PG8_SB(1, 1), b3 + hstep, voffB); PG8_STAGE(PG8_SA(1, 0), a3, voffA);
;             PG8_WAIT_V(8); PG8_WAIT_L(0); PG8_BAR; PG8_MMA(1, 0, At, B0); PG8_MMA(1, 1, At, B1); PG8_BAR; PG8_SCHED;
	s_add_i32 s68, 0, 0x18000
	v_add_u32_e32 v159, s68, v239
	s_add_i32 s69, 0, 0x1c000
	ds_read_b128 v[130:133], v159
	ds_read_b128 v[134:137], v159 offset:1024
	ds_read_b128 v[138:141], v159 offset:2048
	ds_read_b128 v[162:165], v159 offset:3072
	v_add_u32_e32 v159, s69, v239
	ds_read_b128 v[166:169], v159
	ds_read_b128 v[170:173], v159 offset:1024
	ds_read_b128 v[186:189], v159 offset:2048
	ds_read_b128 v[190:193], v159 offset:3072
	s_add_u32 s54, s54, 0x40000
	s_addc_u32 s55, s55, 0
	s_mov_b32 m0, s15
	ds_read_b128 v[194:197], v240 offset:32768
	ds_read_b128 v[198:201], v240 offset:33792
	ds_read_b128 v[202:205], v240 offset:34816
	ds_read_b128 v[206:209], v240 offset:35840
	ds_read_b128 v[210:213], v240 offset:36864
	ds_read_b128 v[214:217], v240 offset:37888
	ds_read_b128 v[218:221], v240 offset:38912
	ds_read_b128 v[222:225], v240 offset:39936
	global_load_lds_dwordx4 v148, s[54:55]
	s_mov_b32 m0, s37
	s_nop 0
	global_load_lds_dwordx4 v144, s[54:55]
	s_waitcnt vmcnt(8)
	s_waitcnt lgkmcnt(0)
	s_barrier
	s_setprio 1
	s_waitcnt lgkmcnt(0)
	v_mfma_f32_16x16x32_f16 v[124:127], v[130:133], v[194:197], v[124:127]
	v_mfma_f32_16x16x32_f16 v[120:123], v[138:141], v[194:197], v[120:123]
	v_mfma_f32_16x16x32_f16 v[116:119], v[130:133], v[202:205], v[116:119]
	v_mfma_f32_16x16x32_f16 v[112:115], v[138:141], v[202:205], v[112:115]
	v_mfma_f32_16x16x32_f16 v[108:111], v[130:133], v[210:213], v[108:111]
	v_mfma_f32_16x16x32_f16 v[104:107], v[138:141], v[210:213], v[104:107]
	v_mfma_f32_16x16x32_f16 v[100:103], v[130:133], v[218:221], v[100:103]
	v_mfma_f32_16x16x32_f16 v[96:99], v[138:141], v[218:221], v[96:99]
	v_mfma_f32_16x16x32_f16 v[124:127], v[134:137], v[198:201], v[124:127]
	v_mfma_f32_16x16x32_f16 v[120:123], v[162:165], v[198:201], v[120:123]
	v_mfma_f32_16x16x32_f16 v[116:119], v[134:137], v[206:209], v[116:119]
	v_mfma_f32_16x16x32_f16 v[112:115], v[162:165], v[206:209], v[112:115]
	v_mfma_f32_16x16x32_f16 v[108:111], v[134:137], v[214:217], v[108:111]
	v_mfma_f32_16x16x32_f16 v[104:107], v[162:165], v[214:217], v[104:107]
	v_mfma_f32_16x16x32_f16 v[100:103], v[134:137], v[222:225], v[100:103]
	v_mfma_f32_16x16x32_f16 v[96:99], v[162:165], v[222:225], v[96:99]
	s_setprio 0
	s_setprio 1
	v_mfma_f32_16x16x32_f16 v[60:63], v[166:169], v[194:197], v[60:63]
	v_mfma_f32_16x16x32_f16 v[56:59], v[186:189], v[194:197], v[56:59]
	v_mfma_f32_16x16x32_f16 v[52:55], v[166:169], v[202:205], v[52:55]
	v_mfma_f32_16x16x32_f16 v[48:51], v[186:189], v[202:205], v[48:51]
	v_mfma_f32_16x16x32_f16 v[44:47], v[166:169], v[210:213], v[44:47]
	v_mfma_f32_16x16x32_f16 v[40:43], v[186:189], v[210:213], v[40:43]
	v_mfma_f32_16x16x32_f16 v[36:39], v[166:169], v[218:221], v[36:39]
	v_mfma_f32_16x16x32_f16 v[32:35], v[186:189], v[218:221], v[32:35]
	v_mfma_f32_16x16x32_f16 v[60:63], v[170:173], v[198:201], v[60:63]
	v_mfma_f32_16x16x32_f16 v[56:59], v[190:193], v[198:201], v[56:59]
	v_mfma_f32_16x16x32_f16 v[52:55], v[170:173], v[206:209], v[52:55]
	v_mfma_f32_16x16x32_f16 v[48:51], v[190:193], v[206:209], v[48:51]
	v_mfma_f32_16x16x32_f16 v[44:47], v[170:173], v[214:217], v[44:47]
	v_mfma_f32_16x16x32_f16 v[40:43], v[190:193], v[214:217], v[40:43]
	v_mfma_f32_16x16x32_f16 v[36:39], v[170:173], v[222:225], v[36:39]
	v_mfma_f32_16x16x32_f16 v[32:35], v[190:193], v[222:225], v[32:35]
	s_setprio 0
	s_barrier
	s_add_i32 s54, s68, s20
	s_mov_b32 m0, s54
	ds_read_b128 v[194:197], v240 offset:49152
	ds_read_b128 v[198:201], v240 offset:50176
	ds_read_b128 v[202:205], v240 offset:51200
	ds_read_b128 v[206:209], v240 offset:52224
	ds_read_b128 v[210:213], v240 offset:53248
	ds_read_b128 v[214:217], v240 offset:54272
	ds_read_b128 v[218:221], v240 offset:55296
	ds_read_b128 v[222:225], v240 offset:56320
	global_load_lds_dwordx4 v146, s[98:99]
	s_add_i32 m0, s54, 0x2000
	s_add_u32 s42, s42, 0x40080
	s_addc_u32 s43, s43, 0
	s_add_i32 s54, s69, s20
	global_load_lds_dwordx4 v142, s[98:99]
	s_mov_b32 m0, s54
	s_nop 0
	global_load_lds_dwordx4 v146, s[42:43]
	s_add_i32 m0, s54, 0x2000
	s_nop 0
	global_load_lds_dwordx4 v142, s[42:43]
	s_mov_b32 m0, s44
	s_nop 0
	global_load_lds_dwordx4 v148, s[100:101]
	s_mov_b32 m0, s45
	s_nop 0
	global_load_lds_dwordx4 v144, s[100:101]
	s_waitcnt vmcnt(8)
	s_waitcnt lgkmcnt(0)
	s_barrier
	s_setprio 1
	s_waitcnt lgkmcnt(0)
	v_mfma_f32_16x16x32_f16 v[92:95], v[130:133], v[194:197], v[92:95]
	v_mfma_f32_16x16x32_f16 v[88:91], v[138:141], v[194:197], v[88:91]
	v_mfma_f32_16x16x32_f16 v[84:87], v[130:133], v[202:205], v[84:87]
	v_mfma_f32_16x16x32_f16 v[80:83], v[138:141], v[202:205], v[80:83]
	v_mfma_f32_16x16x32_f16 v[76:79], v[130:133], v[210:213], v[76:79]
	v_mfma_f32_16x16x32_f16 v[72:75], v[138:141], v[210:213], v[72:75]
	v_mfma_f32_16x16x32_f16 v[68:71], v[130:133], v[218:221], v[68:71]
	v_mfma_f32_16x16x32_f16 v[64:67], v[138:141], v[218:221], v[64:67]
	v_mfma_f32_16x16x32_f16 v[92:95], v[134:137], v[198:201], v[92:95]
	v_mfma_f32_16x16x32_f16 v[88:91], v[162:165], v[198:201], v[88:91]
	v_mfma_f32_16x16x32_f16 v[84:87], v[134:137], v[206:209], v[84:87]
	v_mfma_f32_16x16x32_f16 v[80:83], v[162:165], v[206:209], v[80:83]
	v_mfma_f32_16x16x32_f16 v[76:79], v[134:137], v[214:217], v[76:79]
	v_mfma_f32_16x16x32_f16 v[72:75], v[162:165], v[214:217], v[72:75]
	v_mfma_f32_16x16x32_f16 v[68:71], v[134:137], v[222:225], v[68:71]
	v_mfma_f32_16x16x32_f16 v[64:67], v[162:165], v[222:225], v[64:67]
	s_setprio 0
	s_setprio 1
	v_mfma_f32_16x16x32_f16 v[28:31], v[166:169], v[194:197], v[28:31]
	v_mfma_f32_16x16x32_f16 v[24:27], v[186:189], v[194:197], v[24:27]
	v_mfma_f32_16x16x32_f16 v[20:23], v[166:169], v[202:205], v[20:23]
	v_mfma_f32_16x16x32_f16 v[16:19], v[186:189], v[202:205], v[16:19]
	v_mfma_f32_16x16x32_f16 v[12:15], v[166:169], v[210:213], v[12:15]
	v_mfma_f32_16x16x32_f16 v[8:11], v[186:189], v[210:213], v[8:11]
	v_mfma_f32_16x16x32_f16 v[4:7], v[166:169], v[218:221], v[4:7]
	v_mfma_f32_16x16x32_f16 v[0:3], v[186:189], v[218:221], v[0:3]
	v_mfma_f32_16x16x32_f16 v[28:31], v[170:173], v[198:201], v[28:31]
	v_mfma_f32_16x16x32_f16 v[24:27], v[190:193], v[198:201], v[24:27]
	v_mfma_f32_16x16x32_f16 v[20:23], v[170:173], v[206:209], v[20:23]
	v_mfma_f32_16x16x32_f16 v[16:19], v[190:193], v[206:209], v[16:19]
	v_mfma_f32_16x16x32_f16 v[12:15], v[170:173], v[214:217], v[12:15]
	v_mfma_f32_16x16x32_f16 v[8:11], v[190:193], v[214:217], v[8:11]
	v_mfma_f32_16x16x32_f16 v[4:7], v[170:173], v[222:225], v[4:7]
	v_mfma_f32_16x16x32_f16 v[0:3], v[190:193], v[222:225], v[0:3]
	s_setprio 0
	s_barrier
	s_add_i32 s67, s67, 2
	s_add_u32 s0, s0, 0x100
	s_addc_u32 s1, s1, 0
	s_add_u32 s59, s59, 0x100
	s_addc_u32 s61, s61, 0
	s_cmp_gt_u32 s67, 13
	s_cbranch_scc0 .LBB0_256
	s_and_b64 vcc, exec, s[8:9]
	s_cbranch_vccz .LBB0_259
	s_barrier

; #define PG8_STAGE(bufoff, gbase, voff) do { _Pragma("unroll") for (int _i = 0; _i < 2; ++_i) \
;         __builtin_amdgcn_global_load_lds((const unsigned*)((const char*)(gbase) + (voff)[_i]), (PG8_LAS unsigned*)(lds + (bufoff) + ldsw + _i * 8192), 16, 0, 0); } while (0)
; #define PG8_LDA(dst, b, h) do { _Pragma("unroll") for (int m = 0; m < 4; ++m) _Pragma("unroll") for (int k = 0; k < 2; ++k) dst[m][k] = *(const PG8_LAS bf16x8*)(lds + PG8_SA(b, h) + aoff + m * 2048 + k * 1024); } while (0)
; #define PG8_LDB(dst, b, h) do { _Pragma("unroll") for (int n = 0; n < 2; ++n) _Pragma("unroll") for (int k = 0; k < 2; ++k) dst[n][k] = *(const PG8_LAS bf16x8*)(lds + PG8_SB(b, h) + boff + n * 2048 + k * 1024); } while (0)
; #define PG8_WAIT_V(n) asm volatile("s_waitcnt vmcnt(" #n ")" ::: "memory")
; #define PG8_BAR __builtin_amdgcn_s_barrier()
; template <class Epi, class Sched, bool ALIGN_EPI = false, bool SP2 = false, bool F16 = false>
; __device__ __forceinline__ void gemm_phase(PG8_LAS unsigned char* lds, const Gemm g, const Sched& S, const Epi& E) {
;     ...
;         const bool has_next = S.next(ui + 1, nxt);
;         const char* nA = has_next ? (const char*)g.A + (size_t)nxt.pm * tstep : cA; const char* nB = has_next ? (const char*)g.Bt + (size_t)nxt.pn * tstep + (nxt.pm >= g.mhalf ? g.bstride : (size_t)0) : cB;
;         for (int t = 0; t < nt; t += 2) {
;             if constexpr (Epi::KHOOK) { if (t == 4 || t == 10) E.khook(acc, cur, t, wr, fr); }
;             const bool last = (t == nt - 2);
;             const char* a1 = cA + (size_t)(t + 1) * kstep;
;             const char* a2 = last ? nA : cA + (size_t)(t + 2) * kstep; const char* b2 = last ? nB : cB + (size_t)(t + 2) * kstep;
;             const char* a3 = a2 + kstep; const char* b3 = b2 + kstep;
;             if (last && has_next) S.a_ready(nxt);
;             if constexpr (SP2) {
;             PG8_LDB(B0, 0, 0); PG8_LDB(B1, 0, 1); PG8_SCHED; PG8_LDA(At, 0, 0); PG8_STAGE(PG8_SA(1, 1), a1 + hstep, voffA);
;             PG8_WAIT_V(8); PG8_WAIT_L(0); PG8_BAR; PG8_MMA(0, 0, At, B0); PG8_MMA(0, 1, At, B1); PG8_BAR; PG8_SCHED;
;             PG8_LDA(At, 0, 1); PG8_STAGE(PG8_SB(0, 0), b2, voffB); PG8_STAGE(PG8_SB(0, 1), b2 + hstep, voffB); PG8_STAGE(PG8_SA(0, 0), a2, voffA);
;             PG8_WAIT_V(8); PG8_WAIT_L(0); PG8_BAR; PG8_MMA(1, 0, At, B0); PG8_MMA(1, 1, At, B1); PG8_BAR; PG8_SCHED;
.LBB0_904:
	s_add_u32 s56, s54, 0xfffc0080
	s_addc_u32 s57, s55, -1
	s_add_i32 s62, 0, 0x10000
	s_cmp_eq_u32 s61, 12
	s_cselect_b32 s59, s4, s57
	s_cselect_b32 s58, s5, s56
	s_cselect_b32 s57, s37, s60
	s_cselect_b32 s56, s47, s49
	s_add_i32 s64, 0, 0x14000
	v_add_u32_e32 v44, s62, v163
	v_add_u32_e32 v160, s64, v163
	ds_read_b128 v[32:35], v44
	ds_read_b128 v[36:39], v44 offset:1024
	ds_read_b128 v[40:43], v44 offset:2048
	ds_read_b128 v[44:47], v44 offset:3072
	ds_read_b128 v[156:159], v160
	ds_read_b128 v[168:171], v160 offset:1024
	ds_read_b128 v[186:189], v160 offset:2048
	ds_read_b128 v[190:193], v160 offset:3072
	s_add_i32 m0, s9, 0xc000
	ds_read_b128 v[194:197], v165
	ds_read_b128 v[198:201], v165 offset:1024
	ds_read_b128 v[202:205], v165 offset:2048
	ds_read_b128 v[206:209], v165 offset:3072
	ds_read_b128 v[210:213], v165 offset:4096
	ds_read_b128 v[214:217], v165 offset:5120
	ds_read_b128 v[218:221], v165 offset:6144
	ds_read_b128 v[222:225], v165 offset:7168
	global_load_lds_dwordx4 v152, s[54:55]
	s_add_i32 m0, s9, 0xe000
	s_nop 0
	global_load_lds_dwordx4 v154, s[54:55]
	s_waitcnt vmcnt(8)
	s_waitcnt lgkmcnt(0)
	s_barrier
	s_setprio 1
	s_waitcnt lgkmcnt(0)
	v_mfma_f32_16x16x32_f16 v[142:145], v[32:35], v[194:197], v[142:145]
	v_mfma_f32_16x16x32_f16 v[138:141], v[40:43], v[194:197], v[138:141]
	v_mfma_f32_16x16x32_f16 v[124:127], v[32:35], v[202:205], v[124:127]
	v_mfma_f32_16x16x32_f16 v[120:123], v[40:43], v[202:205], v[120:123]
	v_mfma_f32_16x16x32_f16 v[108:111], v[32:35], v[210:213], v[108:111]
	v_mfma_f32_16x16x32_f16 v[104:107], v[40:43], v[210:213], v[104:107]
	v_mfma_f32_16x16x32_f16 v[92:95], v[32:35], v[218:221], v[92:95]
	v_mfma_f32_16x16x32_f16 v[88:91], v[40:43], v[218:221], v[88:91]
	v_mfma_f32_16x16x32_f16 v[142:145], v[36:39], v[198:201], v[142:145]
	v_mfma_f32_16x16x32_f16 v[138:141], v[44:47], v[198:201], v[138:141]
	v_mfma_f32_16x16x32_f16 v[124:127], v[36:39], v[206:209], v[124:127]
	v_mfma_f32_16x16x32_f16 v[120:123], v[44:47], v[206:209], v[120:123]
	v_mfma_f32_16x16x32_f16 v[108:111], v[36:39], v[214:217], v[108:111]
	v_mfma_f32_16x16x32_f16 v[104:107], v[44:47], v[214:217], v[104:107]
	v_mfma_f32_16x16x32_f16 v[92:95], v[36:39], v[222:225], v[92:95]
	v_mfma_f32_16x16x32_f16 v[88:91], v[44:47], v[222:225], v[88:91]
	s_setprio 0
	s_setprio 1
	v_mfma_f32_16x16x32_f16 v[134:137], v[156:159], v[194:197], v[134:137]
	v_mfma_f32_16x16x32_f16 v[130:133], v[186:189], v[194:197], v[130:133]
	v_mfma_f32_16x16x32_f16 v[116:119], v[156:159], v[202:205], v[116:119]
	v_mfma_f32_16x16x32_f16 v[112:115], v[186:189], v[202:205], v[112:115]
	v_mfma_f32_16x16x32_f16 v[100:103], v[156:159], v[210:213], v[100:103]
	v_mfma_f32_16x16x32_f16 v[96:99], v[186:189], v[210:213], v[96:99]
	v_mfma_f32_16x16x32_f16 v[84:87], v[156:159], v[218:221], v[84:87]
	v_mfma_f32_16x16x32_f16 v[80:83], v[186:189], v[218:221], v[80:83]
	v_mfma_f32_16x16x32_f16 v[134:137], v[168:171], v[198:201], v[134:137]
	v_mfma_f32_16x16x32_f16 v[130:133], v[190:193], v[198:201], v[130:133]
	v_mfma_f32_16x16x32_f16 v[116:119], v[168:171], v[206:209], v[116:119]
	v_mfma_f32_16x16x32_f16 v[112:115], v[190:193], v[206:209], v[112:115]
	v_mfma_f32_16x16x32_f16 v[100:103], v[168:171], v[214:217], v[100:103]
	v_mfma_f32_16x16x32_f16 v[96:99], v[190:193], v[214:217], v[96:99]
	v_mfma_f32_16x16x32_f16 v[84:87], v[168:171], v[222:225], v[84:87]
	v_mfma_f32_16x16x32_f16 v[80:83], v[190:193], v[222:225], v[80:83]
	s_setprio 0
	s_barrier
	s_add_u32 s98, s56, s16
	s_addc_u32 s99, s57, s17
	s_add_u32 s100, s58, s16
	s_addc_u32 s101, s59, s17
	s_add_i32 s62, s62, s8
	s_mov_b32 m0, s62
	ds_read_b128 v[194:197], v165 offset:16384
	ds_read_b128 v[198:201], v165 offset:17408
	ds_read_b128 v[202:205], v165 offset:18432
	ds_read_b128 v[206:209], v165 offset:19456
	ds_read_b128 v[210:213], v165 offset:20480
	ds_read_b128 v[214:217], v165 offset:21504
	ds_read_b128 v[218:221], v165 offset:22528
	ds_read_b128 v[222:225], v165 offset:23552
	global_load_lds_dwordx4 v128, s[56:57]
	s_add_i32 m0, s62, 0x2000
	s_add_u32 s62, s56, 0x40000
	s_addc_u32 s63, s57, 0
	s_add_i32 s64, s64, s8
	global_load_lds_dwordx4 v146, s[56:57]
	s_mov_b32 m0, s64
	s_nop 0
	global_load_lds_dwordx4 v128, s[62:63]
	s_add_i32 m0, s64, 0x2000
	s_nop 0
	global_load_lds_dwordx4 v146, s[62:63]
	s_mov_b32 m0, s9
	s_nop 0
	global_load_lds_dwordx4 v150, s[58:59]
	s_mov_b32 m0, s10
	s_nop 0
	global_load_lds_dwordx4 v148, s[58:59]
	s_waitcnt vmcnt(8)
	s_waitcnt lgkmcnt(0)
	s_barrier
	s_setprio 1
	s_waitcnt lgkmcnt(0)
	v_mfma_f32_16x16x32_f16 v[76:79], v[32:35], v[194:197], v[76:79]
	v_mfma_f32_16x16x32_f16 v[72:75], v[40:43], v[194:197], v[72:75]
	v_mfma_f32_16x16x32_f16 v[60:63], v[32:35], v[202:205], v[60:63]
	v_mfma_f32_16x16x32_f16 v[56:59], v[40:43], v[202:205], v[56:59]
	v_mfma_f32_16x16x32_f16 v[28:31], v[32:35], v[210:213], v[28:31]
	v_mfma_f32_16x16x32_f16 v[24:27], v[40:43], v[210:213], v[24:27]
	v_mfma_f32_16x16x32_f16 v[12:15], v[32:35], v[218:221], v[12:15]
	v_mfma_f32_16x16x32_f16 v[8:11], v[40:43], v[218:221], v[8:11]
	v_mfma_f32_16x16x32_f16 v[76:79], v[36:39], v[198:201], v[76:79]
	v_mfma_f32_16x16x32_f16 v[72:75], v[44:47], v[198:201], v[72:75]
	v_mfma_f32_16x16x32_f16 v[60:63], v[36:39], v[206:209], v[60:63]
	v_mfma_f32_16x16x32_f16 v[56:59], v[44:47], v[206:209], v[56:59]
	v_mfma_f32_16x16x32_f16 v[28:31], v[36:39], v[214:217], v[28:31]
	v_mfma_f32_16x16x32_f16 v[24:27], v[44:47], v[214:217], v[24:27]
	v_mfma_f32_16x16x32_f16 v[12:15], v[36:39], v[222:225], v[12:15]
	v_mfma_f32_16x16x32_f16 v[8:11], v[44:47], v[222:225], v[8:11]
	s_setprio 0
	s_setprio 1
	v_mfma_f32_16x16x32_f16 v[20:23], v[156:159], v[210:213], v[20:23]
	v_mfma_f32_16x16x32_f16 v[16:19], v[186:189], v[210:213], v[16:19]
	v_mfma_f32_16x16x32_f16 v[4:7], v[156:159], v[218:221], v[4:7]
	v_mfma_f32_16x16x32_f16 v[0:3], v[186:189], v[218:221], v[0:3]
	v_mfma_f32_16x16x32_f16 v[32:35], v[156:159], v[194:197], v[68:71]
	v_mfma_f32_16x16x32_f16 v[36:39], v[186:189], v[194:197], v[64:67]
	v_mfma_f32_16x16x32_f16 v[40:43], v[156:159], v[202:205], v[52:55]
	v_mfma_f32_16x16x32_f16 v[44:47], v[186:189], v[202:205], v[48:51]
	v_mfma_f32_16x16x32_f16 v[20:23], v[168:171], v[214:217], v[20:23]
	v_mfma_f32_16x16x32_f16 v[16:19], v[190:193], v[214:217], v[16:19]
	v_mfma_f32_16x16x32_f16 v[4:7], v[168:171], v[222:225], v[4:7]
	v_mfma_f32_16x16x32_f16 v[0:3], v[190:193], v[222:225], v[0:3]
	v_mfma_f32_16x16x32_f16 v[32:35], v[168:171], v[198:201], v[32:35]
	v_mfma_f32_16x16x32_f16 v[36:39], v[190:193], v[198:201], v[36:39]
	v_mfma_f32_16x16x32_f16 v[40:43], v[168:171], v[206:209], v[40:43]
	v_mfma_f32_16x16x32_f16 v[44:47], v[190:193], v[206:209], v[44:47]
	s_setprio 0
	s_barrier
; #define PG8_STAGE(bufoff, gbase, voff) do { _Pragma("unroll") for (int _i = 0; _i < 2; ++_i) \
;         __builtin_amdgcn_global_load_lds((const unsigned*)((const char*)(gbase) + (voff)[_i]), (PG8_LAS unsigned*)(lds + (bufoff) + ldsw + _i * 8192), 16, 0, 0); } while (0)
; #define PG8_LDA(dst, b, h) do { _Pragma("unroll") for (int m = 0; m < 4; ++m) _Pragma("unroll") for (int k = 0; k < 2; ++k) dst[m][k] = *(const PG8_LAS bf16x8*)(lds + PG8_SA(b, h) + aoff + m * 2048 + k * 1024); } while (0)
; #define PG8_LDB(dst, b, h) do { _Pragma("unroll") for (int n = 0; n < 2; ++n) _Pragma("unroll") for (int k = 0; k < 2; ++k) dst[n][k] = *(const PG8_LAS bf16x8*)(lds + PG8_SB(b, h) + boff + n * 2048 + k * 1024); } while (0)
; #define PG8_WAIT_V(n) asm volatile("s_waitcnt vmcnt(" #n ")" ::: "memory")
; template <class Epi, class Sched, bool ALIGN_EPI = false, bool SP2 = false, bool F16 = false>
; __device__ __forceinline__ void gemm_phase(PG8_LAS unsigned char* lds, const Gemm g, const Sched& S, const Epi& E) {
;     ...
;             const char* a1 = cA + (size_t)(t + 1) * kstep;
;             const char* a2 = last ? nA : cA + (size_t)(t + 2) * kstep; const char* b2 = last ? nB : cB + (size_t)(t + 2) * kstep;
;             const char* a3 = a2 + kstep; const char* b3 = b2 + kstep;
;             if (last && has_next) S.a_ready(nxt);
;             if constexpr (SP2) {
;             PG8_LDB(B0, 0, 0); PG8_LDB(B1, 0, 1); PG8_SCHED; PG8_LDA(At, 0, 0); PG8_STAGE(PG8_SA(1, 1), a1 + hstep, voffA);
;             PG8_WAIT_V(8); PG8_WAIT_L(0); PG8_BAR; PG8_MMA(0, 0, At, B0); PG8_MMA(0, 1, At, B1); PG8_BAR; PG8_SCHED;
;             PG8_LDA(At, 0, 1); PG8_STAGE(PG8_SB(0, 0), b2, voffB); PG8_STAGE(PG8_SB(0, 1), b2 + hstep, voffB); PG8_STAGE(PG8_SA(0, 0), a2, voffA);
;             PG8_WAIT_V(8); PG8_WAIT_L(0); PG8_BAR; PG8_MMA(1, 0, At, B0); PG8_MMA(1, 1, At, B1); PG8_BAR; PG8_SCHED;
;             PG8_LDB(B0, 1, 0); PG8_LDB(B1, 1, 1); PG8_SCHED; PG8_LDA(At, 1, 0); PG8_STAGE(PG8_SA(0, 1), a2 + hstep, voffA);
;             PG8_WAIT_V(8); PG8_WAIT_L(0); PG8_BAR; PG8_MMA(0, 0, At, B0); PG8_MMA(0, 1, At, B1); PG8_BAR; PG8_SCHED;
;             PG8_LDA(At, 1, 1); PG8_STAGE(PG8_SB(1, 0), b3, voffB); PG8_STAGE(PG8_SB(1, 1), b3 + hstep, voffB); PG8_STAGE(PG8_SA(1, 0), a3, voffA);
;             PG8_WAIT_V(8); PG8_WAIT_L(0); PG8_BAR; PG8_MMA(1, 0, At, B0); PG8_MMA(1, 1, At, B1); PG8_BAR; PG8_SCHED;
	s_add_i32 s62, 0, 0x18000
	s_add_i32 s63, 0, 0x1c000
	v_add_u32_e32 v68, s62, v163
	v_add_u32_e32 v167, s63, v163
	ds_read_b128 v[48:51], v68
	ds_read_b128 v[52:55], v68 offset:1024
	ds_read_b128 v[64:67], v68 offset:2048
	ds_read_b128 v[68:71], v68 offset:3072
	ds_read_b128 v[156:159], v167
	ds_read_b128 v[168:171], v167 offset:1024
	ds_read_b128 v[186:189], v167 offset:2048
	ds_read_b128 v[190:193], v167 offset:3072
	s_add_u32 s58, s58, 0x40000
	s_addc_u32 s59, s59, 0
	s_mov_b32 m0, s11
	ds_read_b128 v[194:197], v165 offset:32768
	ds_read_b128 v[198:201], v165 offset:33792
	ds_read_b128 v[202:205], v165 offset:34816
	ds_read_b128 v[206:209], v165 offset:35840
	ds_read_b128 v[210:213], v165 offset:36864
	ds_read_b128 v[214:217], v165 offset:37888
	ds_read_b128 v[218:221], v165 offset:38912
	ds_read_b128 v[222:225], v165 offset:39936
	global_load_lds_dwordx4 v150, s[58:59]
	s_mov_b32 m0, s13
	s_nop 0
	global_load_lds_dwordx4 v148, s[58:59]
	s_waitcnt vmcnt(8)
	s_waitcnt lgkmcnt(0)
	s_barrier
	s_setprio 1
	s_waitcnt lgkmcnt(0)
	v_mfma_f32_16x16x32_f16 v[142:145], v[48:51], v[194:197], v[142:145]
	v_mfma_f32_16x16x32_f16 v[138:141], v[64:67], v[194:197], v[138:141]
	v_mfma_f32_16x16x32_f16 v[124:127], v[48:51], v[202:205], v[124:127]
	v_mfma_f32_16x16x32_f16 v[120:123], v[64:67], v[202:205], v[120:123]
	v_mfma_f32_16x16x32_f16 v[108:111], v[48:51], v[210:213], v[108:111]
	v_mfma_f32_16x16x32_f16 v[104:107], v[64:67], v[210:213], v[104:107]
	v_mfma_f32_16x16x32_f16 v[92:95], v[48:51], v[218:221], v[92:95]
	v_mfma_f32_16x16x32_f16 v[88:91], v[64:67], v[218:221], v[88:91]
	v_mfma_f32_16x16x32_f16 v[142:145], v[52:55], v[198:201], v[142:145]
	v_mfma_f32_16x16x32_f16 v[138:141], v[68:71], v[198:201], v[138:141]
	v_mfma_f32_16x16x32_f16 v[124:127], v[52:55], v[206:209], v[124:127]
	v_mfma_f32_16x16x32_f16 v[120:123], v[68:71], v[206:209], v[120:123]
	v_mfma_f32_16x16x32_f16 v[108:111], v[52:55], v[214:217], v[108:111]
	v_mfma_f32_16x16x32_f16 v[104:107], v[68:71], v[214:217], v[104:107]
	v_mfma_f32_16x16x32_f16 v[92:95], v[52:55], v[222:225], v[92:95]
	v_mfma_f32_16x16x32_f16 v[88:91], v[68:71], v[222:225], v[88:91]
	s_setprio 0
	s_setprio 1
	v_mfma_f32_16x16x32_f16 v[134:137], v[156:159], v[194:197], v[134:137]
	v_mfma_f32_16x16x32_f16 v[130:133], v[186:189], v[194:197], v[130:133]
	v_mfma_f32_16x16x32_f16 v[116:119], v[156:159], v[202:205], v[116:119]
	v_mfma_f32_16x16x32_f16 v[112:115], v[186:189], v[202:205], v[112:115]
	v_mfma_f32_16x16x32_f16 v[100:103], v[156:159], v[210:213], v[100:103]
	v_mfma_f32_16x16x32_f16 v[96:99], v[186:189], v[210:213], v[96:99]
	v_mfma_f32_16x16x32_f16 v[84:87], v[156:159], v[218:221], v[84:87]
	v_mfma_f32_16x16x32_f16 v[80:83], v[186:189], v[218:221], v[80:83]
	v_mfma_f32_16x16x32_f16 v[134:137], v[168:171], v[198:201], v[134:137]
	v_mfma_f32_16x16x32_f16 v[130:133], v[190:193], v[198:201], v[130:133]
	v_mfma_f32_16x16x32_f16 v[116:119], v[168:171], v[206:209], v[116:119]
	v_mfma_f32_16x16x32_f16 v[112:115], v[190:193], v[206:209], v[112:115]
	v_mfma_f32_16x16x32_f16 v[100:103], v[168:171], v[214:217], v[100:103]
	v_mfma_f32_16x16x32_f16 v[96:99], v[190:193], v[214:217], v[96:99]
	v_mfma_f32_16x16x32_f16 v[84:87], v[168:171], v[222:225], v[84:87]
	v_mfma_f32_16x16x32_f16 v[80:83], v[190:193], v[222:225], v[80:83]
	s_setprio 0
	s_barrier
	s_add_i32 s58, s62, s8
	s_mov_b32 m0, s58
	ds_read_b128 v[194:197], v165 offset:49152
	ds_read_b128 v[198:201], v165 offset:50176
	ds_read_b128 v[202:205], v165 offset:51200
	ds_read_b128 v[206:209], v165 offset:52224
	ds_read_b128 v[210:213], v165 offset:53248
	ds_read_b128 v[214:217], v165 offset:54272
	ds_read_b128 v[218:221], v165 offset:55296
	ds_read_b128 v[222:225], v165 offset:56320
	global_load_lds_dwordx4 v128, s[98:99]
	s_add_i32 m0, s58, 0x2000
	s_add_u32 s56, s56, 0x40080
	s_addc_u32 s57, s57, 0
	s_add_i32 s58, s63, s8
	global_load_lds_dwordx4 v146, s[98:99]
	s_mov_b32 m0, s58
	s_nop 0
	global_load_lds_dwordx4 v128, s[56:57]
	s_add_i32 m0, s58, 0x2000
	s_nop 0
	global_load_lds_dwordx4 v146, s[56:57]
	s_mov_b32 m0, s20
	s_nop 0
	global_load_lds_dwordx4 v150, s[100:101]
	s_mov_b32 m0, s21
	s_nop 0
	global_load_lds_dwordx4 v148, s[100:101]
	s_waitcnt vmcnt(8)
	s_waitcnt lgkmcnt(0)
	s_barrier
	s_setprio 1
	s_waitcnt lgkmcnt(0)
	v_mfma_f32_16x16x32_f16 v[76:79], v[48:51], v[194:197], v[76:79]
	v_mfma_f32_16x16x32_f16 v[72:75], v[64:67], v[194:197], v[72:75]
	v_mfma_f32_16x16x32_f16 v[60:63], v[48:51], v[202:205], v[60:63]
	v_mfma_f32_16x16x32_f16 v[56:59], v[64:67], v[202:205], v[56:59]
	v_mfma_f32_16x16x32_f16 v[28:31], v[48:51], v[210:213], v[28:31]
	v_mfma_f32_16x16x32_f16 v[24:27], v[64:67], v[210:213], v[24:27]
	v_mfma_f32_16x16x32_f16 v[12:15], v[48:51], v[218:221], v[12:15]
	v_mfma_f32_16x16x32_f16 v[8:11], v[64:67], v[218:221], v[8:11]
	v_mfma_f32_16x16x32_f16 v[76:79], v[52:55], v[198:201], v[76:79]
	v_mfma_f32_16x16x32_f16 v[72:75], v[68:71], v[198:201], v[72:75]
	v_mfma_f32_16x16x32_f16 v[60:63], v[52:55], v[206:209], v[60:63]
	v_mfma_f32_16x16x32_f16 v[56:59], v[68:71], v[206:209], v[56:59]
	v_mfma_f32_16x16x32_f16 v[28:31], v[52:55], v[214:217], v[28:31]
	v_mfma_f32_16x16x32_f16 v[24:27], v[68:71], v[214:217], v[24:27]
	v_mfma_f32_16x16x32_f16 v[12:15], v[52:55], v[222:225], v[12:15]
	v_mfma_f32_16x16x32_f16 v[8:11], v[68:71], v[222:225], v[8:11]
	s_setprio 0
	s_setprio 1
	v_mfma_f32_16x16x32_f16 v[32:35], v[156:159], v[194:197], v[32:35]
	v_mfma_f32_16x16x32_f16 v[68:71], v[168:171], v[198:201], v[32:35]
	v_mfma_f32_16x16x32_f16 v[32:35], v[186:189], v[194:197], v[36:39]
	v_mfma_f32_16x16x32_f16 v[64:67], v[190:193], v[198:201], v[32:35]
	v_mfma_f32_16x16x32_f16 v[32:35], v[156:159], v[202:205], v[40:43]
	v_mfma_f32_16x16x32_f16 v[52:55], v[168:171], v[206:209], v[32:35]
	v_mfma_f32_16x16x32_f16 v[32:35], v[186:189], v[202:205], v[44:47]
	v_mfma_f32_16x16x32_f16 v[20:23], v[156:159], v[210:213], v[20:23]
	v_mfma_f32_16x16x32_f16 v[16:19], v[186:189], v[210:213], v[16:19]
	v_mfma_f32_16x16x32_f16 v[4:7], v[156:159], v[218:221], v[4:7]
	v_mfma_f32_16x16x32_f16 v[0:3], v[186:189], v[218:221], v[0:3]
	v_mfma_f32_16x16x32_f16 v[48:51], v[190:193], v[206:209], v[32:35]
	v_mfma_f32_16x16x32_f16 v[20:23], v[168:171], v[214:217], v[20:23]
	v_mfma_f32_16x16x32_f16 v[16:19], v[190:193], v[214:217], v[16:19]
	v_mfma_f32_16x16x32_f16 v[4:7], v[168:171], v[222:225], v[4:7]
	v_mfma_f32_16x16x32_f16 v[0:3], v[190:193], v[222:225], v[0:3]
	s_setprio 0
	s_barrier
	s_add_i32 s61, s61, 2
	s_add_u32 s54, s54, 0x100
	s_addc_u32 s55, s55, 0
	s_add_u32 s49, s49, 0x100
	s_addc_u32 s60, s60, 0
	s_cmp_gt_u32 s61, 13
	s_cbranch_scc0 .LBB0_904
	s_and_b64 vcc, exec, s[44:45]
	s_cbranch_vccz .LBB0_907
	s_barrier

; #define PG8_STAGE(bufoff, gbase, voff) do { _Pragma("unroll") for (int _i = 0; _i < 2; ++_i) \
;         __builtin_amdgcn_global_load_lds((const unsigned*)((const char*)(gbase) + (voff)[_i]), (PG8_LAS unsigned*)(lds + (bufoff) + ldsw + _i * 8192), 16, 0, 0); } while (0)
; #define PG8_LDA(dst, b, h) do { _Pragma("unroll") for (int m = 0; m < 4; ++m) _Pragma("unroll") for (int k = 0; k < 2; ++k) dst[m][k] = *(const PG8_LAS bf16x8*)(lds + PG8_SA(b, h) + aoff + m * 2048 + k * 1024); } while (0)
; #define PG8_LDB(dst, b, h) do { _Pragma("unroll") for (int n = 0; n < 2; ++n) _Pragma("unroll") for (int k = 0; k < 2; ++k) dst[n][k] = *(const PG8_LAS bf16x8*)(lds + PG8_SB(b, h) + boff + n * 2048 + k * 1024); } while (0)
; #define PG8_WAIT_V(n) asm volatile("s_waitcnt vmcnt(" #n ")" ::: "memory")
; #define PG8_BAR __builtin_amdgcn_s_barrier()
; template <class Epi, class Sched, bool ALIGN_EPI = false, bool SP2 = false, bool F16 = false>
; __device__ __forceinline__ void gemm_phase(PG8_LAS unsigned char* lds, const Gemm g, const Sched& S, const Epi& E) {
;     ...
;         const bool has_next = S.next(ui + 1, nxt);
;         const char* nA = has_next ? (const char*)g.A + (size_t)nxt.pm * tstep : cA; const char* nB = has_next ? (const char*)g.Bt + (size_t)nxt.pn * tstep + (nxt.pm >= g.mhalf ? g.bstride : (size_t)0) : cB;
;         for (int t = 0; t < nt; t += 2) {
;             if constexpr (Epi::KHOOK) { if (t == 4 || t == 10) E.khook(acc, cur, t, wr, fr); }
;             const bool last = (t == nt - 2);
;             const char* a1 = cA + (size_t)(t + 1) * kstep;
;             const char* a2 = last ? nA : cA + (size_t)(t + 2) * kstep; const char* b2 = last ? nB : cB + (size_t)(t + 2) * kstep;
;             const char* a3 = a2 + kstep; const char* b3 = b2 + kstep;
;             if (last && has_next) S.a_ready(nxt);
;             if constexpr (SP2) {
;             PG8_LDB(B0, 0, 0); PG8_LDB(B1, 0, 1); PG8_SCHED; PG8_LDA(At, 0, 0); PG8_STAGE(PG8_SA(1, 1), a1 + hstep, voffA);
;             PG8_WAIT_V(8); PG8_WAIT_L(0); PG8_BAR; PG8_MMA(0, 0, At, B0); PG8_MMA(0, 1, At, B1); PG8_BAR; PG8_SCHED;
;             PG8_LDA(At, 0, 1); PG8_STAGE(PG8_SB(0, 0), b2, voffB); PG8_STAGE(PG8_SB(0, 1), b2 + hstep, voffB); PG8_STAGE(PG8_SA(0, 0), a2, voffA);
;             PG8_WAIT_V(8); PG8_WAIT_L(0); PG8_BAR; PG8_MMA(1, 0, At, B0); PG8_MMA(1, 1, At, B1); PG8_BAR; PG8_SCHED;
.LBB0_997:
	s_add_u32 s50, s48, 0x100
	s_addc_u32 s51, s49, 0
	s_add_i32 s59, 0, 0x10000
	s_cmp_eq_u32 s58, 40
	s_cselect_b32 s55, s43, s51
	s_cselect_b32 s54, s42, s50
	s_cselect_b32 s53, s47, s5
	s_cselect_b32 s52, s46, s4
	s_add_i32 s60, 0, 0x14000
	v_add_u32_e32 v142, s59, v224
	v_add_u32_e32 v158, s60, v224
	ds_read_b128 v[130:133], v142
	ds_read_b128 v[134:137], v142 offset:1024
	ds_read_b128 v[138:141], v142 offset:2048
	ds_read_b128 v[142:145], v142 offset:3072
	ds_read_b128 v[146:149], v158
	ds_read_b128 v[150:153], v158 offset:1024
	ds_read_b128 v[154:157], v158 offset:2048
	ds_read_b128 v[158:161], v158 offset:3072
	s_add_i32 m0, s9, 0xc000
	ds_read_b128 v[186:189], v225
	ds_read_b128 v[190:193], v225 offset:1024
	ds_read_b128 v[194:197], v225 offset:2048
	ds_read_b128 v[198:201], v225 offset:3072
	ds_read_b128 v[202:205], v225 offset:4096
	ds_read_b128 v[206:209], v225 offset:5120
	ds_read_b128 v[210:213], v225 offset:6144
	ds_read_b128 v[214:217], v225 offset:7168
	global_load_lds_dwordx4 v168, s[48:49]
	s_add_i32 m0, s9, 0xe000
	s_nop 0
	global_load_lds_dwordx4 v170, s[48:49]
	s_waitcnt vmcnt(8)
	s_waitcnt lgkmcnt(0)
	s_barrier
	s_setprio 1
	s_waitcnt lgkmcnt(0)
	v_mfma_f32_16x16x32_bf16 v[124:127], v[130:133], v[186:189], v[124:127]
	v_mfma_f32_16x16x32_bf16 v[120:123], v[138:141], v[186:189], v[120:123]
	v_mfma_f32_16x16x32_bf16 v[116:119], v[130:133], v[194:197], v[116:119]
	v_mfma_f32_16x16x32_bf16 v[112:115], v[138:141], v[194:197], v[112:115]
	v_mfma_f32_16x16x32_bf16 v[108:111], v[130:133], v[202:205], v[108:111]
	v_mfma_f32_16x16x32_bf16 v[104:107], v[138:141], v[202:205], v[104:107]
	v_mfma_f32_16x16x32_bf16 v[100:103], v[130:133], v[210:213], v[100:103]
	v_mfma_f32_16x16x32_bf16 v[96:99], v[138:141], v[210:213], v[96:99]
	v_mfma_f32_16x16x32_bf16 v[124:127], v[134:137], v[190:193], v[124:127]
	v_mfma_f32_16x16x32_bf16 v[120:123], v[142:145], v[190:193], v[120:123]
	v_mfma_f32_16x16x32_bf16 v[116:119], v[134:137], v[198:201], v[116:119]
	v_mfma_f32_16x16x32_bf16 v[112:115], v[142:145], v[198:201], v[112:115]
	v_mfma_f32_16x16x32_bf16 v[108:111], v[134:137], v[206:209], v[108:111]
	v_mfma_f32_16x16x32_bf16 v[104:107], v[142:145], v[206:209], v[104:107]
	v_mfma_f32_16x16x32_bf16 v[100:103], v[134:137], v[214:217], v[100:103]
	v_mfma_f32_16x16x32_bf16 v[96:99], v[142:145], v[214:217], v[96:99]
	s_setprio 0
	s_setprio 1
	v_mfma_f32_16x16x32_bf16 v[60:63], v[146:149], v[186:189], v[60:63]
	v_mfma_f32_16x16x32_bf16 v[56:59], v[154:157], v[186:189], v[56:59]
	v_mfma_f32_16x16x32_bf16 v[52:55], v[146:149], v[194:197], v[52:55]
	v_mfma_f32_16x16x32_bf16 v[48:51], v[154:157], v[194:197], v[48:51]
	v_mfma_f32_16x16x32_bf16 v[44:47], v[146:149], v[202:205], v[44:47]
	v_mfma_f32_16x16x32_bf16 v[40:43], v[154:157], v[202:205], v[40:43]
	v_mfma_f32_16x16x32_bf16 v[36:39], v[146:149], v[210:213], v[36:39]
	v_mfma_f32_16x16x32_bf16 v[32:35], v[154:157], v[210:213], v[32:35]
	v_mfma_f32_16x16x32_bf16 v[60:63], v[150:153], v[190:193], v[60:63]
	v_mfma_f32_16x16x32_bf16 v[56:59], v[158:161], v[190:193], v[56:59]
	v_mfma_f32_16x16x32_bf16 v[52:55], v[150:153], v[198:201], v[52:55]
	v_mfma_f32_16x16x32_bf16 v[48:51], v[158:161], v[198:201], v[48:51]
	v_mfma_f32_16x16x32_bf16 v[44:47], v[150:153], v[206:209], v[44:47]
	v_mfma_f32_16x16x32_bf16 v[40:43], v[158:161], v[206:209], v[40:43]
	v_mfma_f32_16x16x32_bf16 v[36:39], v[150:153], v[214:217], v[36:39]
	v_mfma_f32_16x16x32_bf16 v[32:35], v[158:161], v[214:217], v[32:35]
	s_setprio 0
	s_barrier
	s_add_u32 s98, s52, s16
	s_addc_u32 s99, s53, s17
	s_add_u32 s100, s54, s16
	s_addc_u32 s101, s55, s17
	s_add_i32 s48, s59, s8
	s_mov_b32 m0, s48
	ds_read_b128 v[186:189], v225 offset:16384
	ds_read_b128 v[190:193], v225 offset:17408
	ds_read_b128 v[194:197], v225 offset:18432
	ds_read_b128 v[198:201], v225 offset:19456
	ds_read_b128 v[202:205], v225 offset:20480
	ds_read_b128 v[206:209], v225 offset:21504
	ds_read_b128 v[210:213], v225 offset:22528
	ds_read_b128 v[214:217], v225 offset:23552
	global_load_lds_dwordx4 v128, s[52:53]
	s_add_i32 m0, s48, 0x2000
	s_add_u32 s48, s52, 0xb0000
	s_addc_u32 s49, s53, 0
	s_add_i32 s59, s60, s8
	global_load_lds_dwordx4 v162, s[52:53]
	s_mov_b32 m0, s59
	s_nop 0
	global_load_lds_dwordx4 v128, s[48:49]
	s_add_i32 m0, s59, 0x2000
	s_nop 0
	global_load_lds_dwordx4 v162, s[48:49]
	s_mov_b32 m0, s9
	s_nop 0
	global_load_lds_dwordx4 v166, s[54:55]
	s_mov_b32 m0, s10
	s_nop 0
	global_load_lds_dwordx4 v164, s[54:55]
	s_waitcnt vmcnt(8)
	s_waitcnt lgkmcnt(0)
	s_barrier
; #define PG8_STAGE(bufoff, gbase, voff) do { _Pragma("unroll") for (int _i = 0; _i < 2; ++_i) \
;         __builtin_amdgcn_global_load_lds((const unsigned*)((const char*)(gbase) + (voff)[_i]), (PG8_LAS unsigned*)(lds + (bufoff) + ldsw + _i * 8192), 16, 0, 0); } while (0)
; #define PG8_LDA(dst, b, h) do { _Pragma("unroll") for (int m = 0; m < 4; ++m) _Pragma("unroll") for (int k = 0; k < 2; ++k) dst[m][k] = *(const PG8_LAS bf16x8*)(lds + PG8_SA(b, h) + aoff + m * 2048 + k * 1024); } while (0)
; #define PG8_LDB(dst, b, h) do { _Pragma("unroll") for (int n = 0; n < 2; ++n) _Pragma("unroll") for (int k = 0; k < 2; ++k) dst[n][k] = *(const PG8_LAS bf16x8*)(lds + PG8_SB(b, h) + boff + n * 2048 + k * 1024); } while (0)
; #define PG8_MMA(ai, bj, At, Bt) do { __builtin_amdgcn_s_setprio(1); _Pragma("unroll") for (int m = 0; m < 4; ++m) _Pragma("unroll") for (int n = 0; n < 2; ++n) _Pragma("unroll") for (int k = 0; k < 2; ++k) \
;         acc[ai][bj][m][n] = mma16<F16>(Bt[n][k], At[m][k], acc[ai][bj][m][n]); __builtin_amdgcn_s_setprio(0); } while (0)
; #define PG8_WAIT_V(n) asm volatile("s_waitcnt vmcnt(" #n ")" ::: "memory")
; #define PG8_WAIT_L(n) asm volatile("s_waitcnt lgkmcnt(" #n ")" ::: "memory")
; #define PG8_BAR __builtin_amdgcn_s_barrier()
; #define PG8_SCHED __builtin_amdgcn_sched_barrier(0)
; template <class Epi, class Sched, bool ALIGN_EPI = false, bool SP2 = false, bool F16 = false>
; __device__ __forceinline__ void gemm_phase(PG8_LAS unsigned char* lds, const Gemm g, const Sched& S, const Epi& E) {
;     ...
;             PG8_WAIT_V(8); PG8_WAIT_L(0); PG8_BAR; PG8_MMA(0, 0, At, B0); PG8_MMA(0, 1, At, B1); PG8_BAR; PG8_SCHED;
;             PG8_LDA(At, 0, 1); PG8_STAGE(PG8_SB(0, 0), b2, voffB); PG8_STAGE(PG8_SB(0, 1), b2 + hstep, voffB); PG8_STAGE(PG8_SA(0, 0), a2, voffA);
;             PG8_WAIT_V(8); PG8_WAIT_L(0); PG8_BAR; PG8_MMA(1, 0, At, B0); PG8_MMA(1, 1, At, B1); PG8_BAR; PG8_SCHED;
;             PG8_LDB(B0, 1, 0); PG8_LDB(B1, 1, 1); PG8_SCHED; PG8_LDA(At, 1, 0); PG8_STAGE(PG8_SA(0, 1), a2 + hstep, voffA);
;             PG8_WAIT_V(8); PG8_WAIT_L(0); PG8_BAR; PG8_MMA(0, 0, At, B0); PG8_MMA(0, 1, At, B1); PG8_BAR; PG8_SCHED;
	s_setprio 1
	s_waitcnt lgkmcnt(0)
	v_mfma_f32_16x16x32_bf16 v[92:95], v[130:133], v[186:189], v[92:95]
	v_mfma_f32_16x16x32_bf16 v[88:91], v[138:141], v[186:189], v[88:91]
	v_mfma_f32_16x16x32_bf16 v[84:87], v[130:133], v[194:197], v[84:87]
	v_mfma_f32_16x16x32_bf16 v[80:83], v[138:141], v[194:197], v[80:83]
	v_mfma_f32_16x16x32_bf16 v[76:79], v[130:133], v[202:205], v[76:79]
	v_mfma_f32_16x16x32_bf16 v[72:75], v[138:141], v[202:205], v[72:75]
	v_mfma_f32_16x16x32_bf16 v[68:71], v[130:133], v[210:213], v[68:71]
	v_mfma_f32_16x16x32_bf16 v[64:67], v[138:141], v[210:213], v[64:67]
	v_mfma_f32_16x16x32_bf16 v[92:95], v[134:137], v[190:193], v[92:95]
	v_mfma_f32_16x16x32_bf16 v[88:91], v[142:145], v[190:193], v[88:91]
	v_mfma_f32_16x16x32_bf16 v[84:87], v[134:137], v[198:201], v[84:87]
	v_mfma_f32_16x16x32_bf16 v[80:83], v[142:145], v[198:201], v[80:83]
	v_mfma_f32_16x16x32_bf16 v[76:79], v[134:137], v[206:209], v[76:79]
	v_mfma_f32_16x16x32_bf16 v[72:75], v[142:145], v[206:209], v[72:75]
	v_mfma_f32_16x16x32_bf16 v[68:71], v[134:137], v[214:217], v[68:71]
	v_mfma_f32_16x16x32_bf16 v[64:67], v[142:145], v[214:217], v[64:67]
	s_setprio 0
	s_setprio 1
	v_mfma_f32_16x16x32_bf16 v[28:31], v[146:149], v[186:189], v[28:31]
	v_mfma_f32_16x16x32_bf16 v[24:27], v[154:157], v[186:189], v[24:27]
	v_mfma_f32_16x16x32_bf16 v[20:23], v[146:149], v[194:197], v[20:23]
	v_mfma_f32_16x16x32_bf16 v[16:19], v[154:157], v[194:197], v[16:19]
	v_mfma_f32_16x16x32_bf16 v[12:15], v[146:149], v[202:205], v[12:15]
	v_mfma_f32_16x16x32_bf16 v[8:11], v[154:157], v[202:205], v[8:11]
	v_mfma_f32_16x16x32_bf16 v[4:7], v[146:149], v[210:213], v[4:7]
	v_mfma_f32_16x16x32_bf16 v[0:3], v[154:157], v[210:213], v[0:3]
	v_mfma_f32_16x16x32_bf16 v[28:31], v[150:153], v[190:193], v[28:31]
	v_mfma_f32_16x16x32_bf16 v[24:27], v[158:161], v[190:193], v[24:27]
	v_mfma_f32_16x16x32_bf16 v[20:23], v[150:153], v[198:201], v[20:23]
	v_mfma_f32_16x16x32_bf16 v[16:19], v[158:161], v[198:201], v[16:19]
	v_mfma_f32_16x16x32_bf16 v[12:15], v[150:153], v[206:209], v[12:15]
	v_mfma_f32_16x16x32_bf16 v[8:11], v[158:161], v[206:209], v[8:11]
	v_mfma_f32_16x16x32_bf16 v[4:7], v[150:153], v[214:217], v[4:7]
	v_mfma_f32_16x16x32_bf16 v[0:3], v[158:161], v[214:217], v[0:3]
	s_setprio 0
	s_barrier
	s_add_i32 s59, 0, 0x18000
	s_add_i32 s60, 0, 0x1c000
	v_add_u32_e32 v142, s59, v224
	v_add_u32_e32 v158, s60, v224
	ds_read_b128 v[130:133], v142
	ds_read_b128 v[134:137], v142 offset:1024
	ds_read_b128 v[138:141], v142 offset:2048
	ds_read_b128 v[142:145], v142 offset:3072
	ds_read_b128 v[146:149], v158
	ds_read_b128 v[150:153], v158 offset:1024
	ds_read_b128 v[154:157], v158 offset:2048
	ds_read_b128 v[158:161], v158 offset:3072
	s_add_u32 s48, s54, 0xb0000
	s_addc_u32 s49, s55, 0
	s_mov_b32 m0, s11
	ds_read_b128 v[186:189], v225 offset:32768
	ds_read_b128 v[190:193], v225 offset:33792
	ds_read_b128 v[194:197], v225 offset:34816
	ds_read_b128 v[198:201], v225 offset:35840
	ds_read_b128 v[202:205], v225 offset:36864
	ds_read_b128 v[206:209], v225 offset:37888
	ds_read_b128 v[210:213], v225 offset:38912
	ds_read_b128 v[214:217], v225 offset:39936
	global_load_lds_dwordx4 v166, s[48:49]
	s_mov_b32 m0, s14
	s_nop 0
	global_load_lds_dwordx4 v164, s[48:49]
	s_waitcnt vmcnt(8)
	s_waitcnt lgkmcnt(0)
	s_barrier
	s_setprio 1
	s_waitcnt lgkmcnt(0)
	v_mfma_f32_16x16x32_bf16 v[124:127], v[130:133], v[186:189], v[124:127]
	v_mfma_f32_16x16x32_bf16 v[120:123], v[138:141], v[186:189], v[120:123]
	v_mfma_f32_16x16x32_bf16 v[116:119], v[130:133], v[194:197], v[116:119]
	v_mfma_f32_16x16x32_bf16 v[112:115], v[138:141], v[194:197], v[112:115]
	v_mfma_f32_16x16x32_bf16 v[108:111], v[130:133], v[202:205], v[108:111]
	v_mfma_f32_16x16x32_bf16 v[104:107], v[138:141], v[202:205], v[104:107]
	v_mfma_f32_16x16x32_bf16 v[100:103], v[130:133], v[210:213], v[100:103]
	v_mfma_f32_16x16x32_bf16 v[96:99], v[138:141], v[210:213], v[96:99]
	v_mfma_f32_16x16x32_bf16 v[124:127], v[134:137], v[190:193], v[124:127]
	v_mfma_f32_16x16x32_bf16 v[120:123], v[142:145], v[190:193], v[120:123]
	v_mfma_f32_16x16x32_bf16 v[116:119], v[134:137], v[198:201], v[116:119]
	v_mfma_f32_16x16x32_bf16 v[112:115], v[142:145], v[198:201], v[112:115]
	v_mfma_f32_16x16x32_bf16 v[108:111], v[134:137], v[206:209], v[108:111]
	v_mfma_f32_16x16x32_bf16 v[104:107], v[142:145], v[206:209], v[104:107]
	v_mfma_f32_16x16x32_bf16 v[100:103], v[134:137], v[214:217], v[100:103]
	v_mfma_f32_16x16x32_bf16 v[96:99], v[142:145], v[214:217], v[96:99]
	s_setprio 0
	s_setprio 1
	v_mfma_f32_16x16x32_bf16 v[60:63], v[146:149], v[186:189], v[60:63]
	v_mfma_f32_16x16x32_bf16 v[56:59], v[154:157], v[186:189], v[56:59]
	v_mfma_f32_16x16x32_bf16 v[52:55], v[146:149], v[194:197], v[52:55]
	v_mfma_f32_16x16x32_bf16 v[48:51], v[154:157], v[194:197], v[48:51]
	v_mfma_f32_16x16x32_bf16 v[44:47], v[146:149], v[202:205], v[44:47]
	v_mfma_f32_16x16x32_bf16 v[40:43], v[154:157], v[202:205], v[40:43]
	v_mfma_f32_16x16x32_bf16 v[36:39], v[146:149], v[210:213], v[36:39]
	v_mfma_f32_16x16x32_bf16 v[32:35], v[154:157], v[210:213], v[32:35]
	v_mfma_f32_16x16x32_bf16 v[60:63], v[150:153], v[190:193], v[60:63]
	v_mfma_f32_16x16x32_bf16 v[56:59], v[158:161], v[190:193], v[56:59]
	v_mfma_f32_16x16x32_bf16 v[52:55], v[150:153], v[198:201], v[52:55]
	v_mfma_f32_16x16x32_bf16 v[48:51], v[158:161], v[198:201], v[48:51]
	v_mfma_f32_16x16x32_bf16 v[44:47], v[150:153], v[206:209], v[44:47]
	v_mfma_f32_16x16x32_bf16 v[40:43], v[158:161], v[206:209], v[40:43]
	v_mfma_f32_16x16x32_bf16 v[36:39], v[150:153], v[214:217], v[36:39]
	v_mfma_f32_16x16x32_bf16 v[32:35], v[158:161], v[214:217], v[32:35]
	s_setprio 0
	s_barrier
; #define PG8_STAGE(bufoff, gbase, voff) do { _Pragma("unroll") for (int _i = 0; _i < 2; ++_i) \
;         __builtin_amdgcn_global_load_lds((const unsigned*)((const char*)(gbase) + (voff)[_i]), (PG8_LAS unsigned*)(lds + (bufoff) + ldsw + _i * 8192), 16, 0, 0); } while (0)
; #define PG8_LDA(dst, b, h) do { _Pragma("unroll") for (int m = 0; m < 4; ++m) _Pragma("unroll") for (int k = 0; k < 2; ++k) dst[m][k] = *(const PG8_LAS bf16x8*)(lds + PG8_SA(b, h) + aoff + m * 2048 + k * 1024); } while (0)
; #define PG8_LDB(dst, b, h) do { _Pragma("unroll") for (int n = 0; n < 2; ++n) _Pragma("unroll") for (int k = 0; k < 2; ++k) dst[n][k] = *(const PG8_LAS bf16x8*)(lds + PG8_SB(b, h) + boff + n * 2048 + k * 1024); } while (0)
; #define PG8_WAIT_V(n) asm volatile("s_waitcnt vmcnt(" #n ")" ::: "memory")
; template <class Epi, class Sched, bool ALIGN_EPI = false, bool SP2 = false, bool F16 = false>
; __device__ __forceinline__ void gemm_phase(PG8_LAS unsigned char* lds, const Gemm g, const Sched& S, const Epi& E) {
;     ...
;             const char* a1 = cA + (size_t)(t + 1) * kstep;
;             const char* a2 = last ? nA : cA + (size_t)(t + 2) * kstep; const char* b2 = last ? nB : cB + (size_t)(t + 2) * kstep;
;             const char* a3 = a2 + kstep; const char* b3 = b2 + kstep;
;             if (last && has_next) S.a_ready(nxt);
;             if constexpr (SP2) {
;             PG8_LDB(B0, 0, 0); PG8_LDB(B1, 0, 1); PG8_SCHED; PG8_LDA(At, 0, 0); PG8_STAGE(PG8_SA(1, 1), a1 + hstep, voffA);
;             PG8_WAIT_V(8); PG8_WAIT_L(0); PG8_BAR; PG8_MMA(0, 0, At, B0); PG8_MMA(0, 1, At, B1); PG8_BAR; PG8_SCHED;
;             PG8_LDA(At, 0, 1); PG8_STAGE(PG8_SB(0, 0), b2, voffB); PG8_STAGE(PG8_SB(0, 1), b2 + hstep, voffB); PG8_STAGE(PG8_SA(0, 0), a2, voffA);
;             PG8_WAIT_V(8); PG8_WAIT_L(0); PG8_BAR; PG8_MMA(1, 0, At, B0); PG8_MMA(1, 1, At, B1); PG8_BAR; PG8_SCHED;
;             PG8_LDB(B0, 1, 0); PG8_LDB(B1, 1, 1); PG8_SCHED; PG8_LDA(At, 1, 0); PG8_STAGE(PG8_SA(0, 1), a2 + hstep, voffA);
;             PG8_WAIT_V(8); PG8_WAIT_L(0); PG8_BAR; PG8_MMA(0, 0, At, B0); PG8_MMA(0, 1, At, B1); PG8_BAR; PG8_SCHED;
;             PG8_LDA(At, 1, 1); PG8_STAGE(PG8_SB(1, 0), b3, voffB); PG8_STAGE(PG8_SB(1, 1), b3 + hstep, voffB); PG8_STAGE(PG8_SA(1, 0), a3, voffA);
;             PG8_WAIT_V(8); PG8_WAIT_L(0); PG8_BAR; PG8_MMA(1, 0, At, B0); PG8_MMA(1, 1, At, B1); PG8_BAR; PG8_SCHED;
	s_add_i32 s48, s59, s8
	s_mov_b32 m0, s48
	ds_read_b128 v[186:189], v225 offset:49152
	ds_read_b128 v[190:193], v225 offset:50176
	ds_read_b128 v[194:197], v225 offset:51200
	ds_read_b128 v[198:201], v225 offset:52224
	ds_read_b128 v[202:205], v225 offset:53248
	ds_read_b128 v[206:209], v225 offset:54272
	ds_read_b128 v[210:213], v225 offset:55296
	ds_read_b128 v[214:217], v225 offset:56320
	global_load_lds_dwordx4 v128, s[98:99]
	s_add_i32 m0, s48, 0x2000
	s_add_u32 s48, s52, 0xb0080
	s_addc_u32 s49, s53, 0
	s_add_i32 s52, s60, s8
	global_load_lds_dwordx4 v162, s[98:99]
	s_mov_b32 m0, s52
	s_nop 0
	global_load_lds_dwordx4 v128, s[48:49]
	s_add_i32 m0, s52, 0x2000
	s_nop 0
	global_load_lds_dwordx4 v162, s[48:49]
	s_mov_b32 m0, s29
	s_nop 0
	global_load_lds_dwordx4 v166, s[100:101]
	s_mov_b32 m0, s30
	s_nop 0
	global_load_lds_dwordx4 v164, s[100:101]
	s_waitcnt vmcnt(8)
	s_waitcnt lgkmcnt(0)
	s_barrier
	s_setprio 1
	s_waitcnt lgkmcnt(0)
	v_mfma_f32_16x16x32_bf16 v[92:95], v[130:133], v[186:189], v[92:95]
	v_mfma_f32_16x16x32_bf16 v[88:91], v[138:141], v[186:189], v[88:91]
	v_mfma_f32_16x16x32_bf16 v[84:87], v[130:133], v[194:197], v[84:87]
	v_mfma_f32_16x16x32_bf16 v[80:83], v[138:141], v[194:197], v[80:83]
	v_mfma_f32_16x16x32_bf16 v[76:79], v[130:133], v[202:205], v[76:79]
	v_mfma_f32_16x16x32_bf16 v[72:75], v[138:141], v[202:205], v[72:75]
	v_mfma_f32_16x16x32_bf16 v[68:71], v[130:133], v[210:213], v[68:71]
	v_mfma_f32_16x16x32_bf16 v[64:67], v[138:141], v[210:213], v[64:67]
	v_mfma_f32_16x16x32_bf16 v[92:95], v[134:137], v[190:193], v[92:95]
	v_mfma_f32_16x16x32_bf16 v[88:91], v[142:145], v[190:193], v[88:91]
	v_mfma_f32_16x16x32_bf16 v[84:87], v[134:137], v[198:201], v[84:87]
	v_mfma_f32_16x16x32_bf16 v[80:83], v[142:145], v[198:201], v[80:83]
	v_mfma_f32_16x16x32_bf16 v[76:79], v[134:137], v[206:209], v[76:79]
	v_mfma_f32_16x16x32_bf16 v[72:75], v[142:145], v[206:209], v[72:75]
	v_mfma_f32_16x16x32_bf16 v[68:71], v[134:137], v[214:217], v[68:71]
	v_mfma_f32_16x16x32_bf16 v[64:67], v[142:145], v[214:217], v[64:67]
	s_setprio 0
	s_setprio 1
	v_mfma_f32_16x16x32_bf16 v[28:31], v[146:149], v[186:189], v[28:31]
	v_mfma_f32_16x16x32_bf16 v[24:27], v[154:157], v[186:189], v[24:27]
	v_mfma_f32_16x16x32_bf16 v[20:23], v[146:149], v[194:197], v[20:23]
	v_mfma_f32_16x16x32_bf16 v[16:19], v[154:157], v[194:197], v[16:19]
	v_mfma_f32_16x16x32_bf16 v[12:15], v[146:149], v[202:205], v[12:15]
	v_mfma_f32_16x16x32_bf16 v[8:11], v[154:157], v[202:205], v[8:11]
	v_mfma_f32_16x16x32_bf16 v[4:7], v[146:149], v[210:213], v[4:7]
	v_mfma_f32_16x16x32_bf16 v[0:3], v[154:157], v[210:213], v[0:3]
	v_mfma_f32_16x16x32_bf16 v[28:31], v[150:153], v[190:193], v[28:31]
	v_mfma_f32_16x16x32_bf16 v[24:27], v[158:161], v[190:193], v[24:27]
	v_mfma_f32_16x16x32_bf16 v[20:23], v[150:153], v[198:201], v[20:23]
	v_mfma_f32_16x16x32_bf16 v[16:19], v[158:161], v[198:201], v[16:19]
	v_mfma_f32_16x16x32_bf16 v[12:15], v[150:153], v[206:209], v[12:15]
	v_mfma_f32_16x16x32_bf16 v[8:11], v[158:161], v[206:209], v[8:11]
	v_mfma_f32_16x16x32_bf16 v[4:7], v[150:153], v[214:217], v[4:7]
	v_mfma_f32_16x16x32_bf16 v[0:3], v[158:161], v[214:217], v[0:3]
	s_setprio 0
	s_barrier
	s_add_i32 s58, s58, 2
	s_add_u32 s4, s4, 0x100
	s_addc_u32 s5, s5, 0
	s_cmp_gt_u32 s58, 41
	s_mov_b64 s[48:49], s[50:51]
	s_cbranch_scc0 .LBB0_997
	s_and_b64 vcc, exec, s[44:45]
	s_cbranch_vccz .LBB0_1000
	s_barrier
